# barrier acquire: L1 invalidate issued at arrival (overlaps the wait; workgroup issues no cached loads until release), removed from the post-release path
# speedup vs baseline: 1.0059x; 1.0021x over previous
; __device__ __forceinline__ unsigned xb_ld(unsigned* p)              { return __hip_atomic_load(p, __ATOMIC_RELAXED, __HIP_MEMORY_SCOPE_AGENT); }
; __device__ __forceinline__ unsigned xb_add(unsigned* p, unsigned v) { return __hip_atomic_fetch_add(p, v, __ATOMIC_RELAXED, __HIP_MEMORY_SCOPE_AGENT); }
; #define XB_SPIN(cond, bar) do { unsigned _sp = 0; while (cond) { __builtin_amdgcn_s_sleep(1); \
;     if ((++_sp & 255u) == 0u) { if (xb_ld(&(bar)[XB_TMO])) break; if (_sp > XB_SPIN_CAP) { atomicAdd(&(bar)[XB_TMO], 1u); break; } } } } while (0)
; __device__ __forceinline__ void xcd_barrier(const XcdBarrier& b) {
;     ...
;         unsigned nloc = b.st[0], nx = b.st[1];
;         if (nloc == 0u) { xcd_barrier_complete(bar, b.x, nloc, nx, b.members); b.st[0] = nloc; b.st[1] = nx; }
;         const unsigned old = xb_add(&bar[XB_XSUB(b.x)], 1u);
;         const unsigned gen = old / nloc;
;         if (old + 1u == (gen + 1u) * nloc) {
;             __builtin_amdgcn_fence(__ATOMIC_RELEASE, "agent");
;             asm volatile("s_waitcnt vmcnt(0)" ::: "memory");
;             const unsigned og = xb_add(&bar[XB_TOP], 1u);
;             const unsigned tg = og / nx;
;             if (og + 1u == (tg + 1u) * nx) xb_add(&bar[XB_TOPGEN], 1u);
;             else XB_SPIN(xb_ld(&bar[XB_TOPGEN]) == tg, bar);
;             __builtin_amdgcn_fence(__ATOMIC_ACQUIRE, "agent");
;             xb_add(&bar[XB_XGEN(b.x)], 1u);
;             asm volatile("s_waitcnt vmcnt(0)" ::: "memory");
;         } else {
;             XB_SPIN(xb_ld(&bar[XB_XGEN(b.x)]) == gen, bar);
;             __builtin_amdgcn_fence(__ATOMIC_ACQUIRE, "agent");
;             asm volatile("s_waitcnt vmcnt(0)" ::: "memory");
;         }
.LBB0_211:
	s_mov_b64 s[4:5], exec
	v_mbcnt_lo_u32_b32 v3, s4, 0
	v_mbcnt_hi_u32_b32 v3, s5, v3
	v_cmp_eq_u32_e32 vcc, 0, v3
	s_and_saveexec_b64 s[2:3], vcc
	s_cbranch_execz .LBB0_213
	s_bcnt1_i32_b64 s4, s[4:5]
	v_mov_b32_e32 v5, s4
	v_readlane_b32 s4, v251, 28
	v_readlane_b32 s5, v251, 29
	s_nop 4
	global_atomic_add v5, v99, v5, s[4:5] sc0
	buffer_inv sc1
.LBB0_213:
	s_or_b64 exec, exec, s[2:3]
	v_cvt_f32_u32_e32 v6, v4
	s_waitcnt vmcnt(1)
	v_readfirstlane_b32 s2, v5
	v_sub_u32_e32 v5, 0, v4
	v_rcp_iflag_f32_e32 v6, v6
	v_add_u32_e32 v7, s2, v3
	v_mul_f32_e32 v6, 0x4f7ffffe, v6
	v_cvt_u32_f32_e32 v6, v6
	v_mul_lo_u32 v3, v5, v6
	v_mul_hi_u32 v3, v6, v3
	v_add_u32_e32 v3, v6, v3
	v_mul_hi_u32 v3, v7, v3
	v_mul_lo_u32 v5, v3, v4
	v_sub_u32_e32 v5, v7, v5
	v_add_u32_e32 v6, 1, v3
	v_cmp_ge_u32_e32 vcc, v5, v4
	s_nop 1
	v_cndmask_b32_e32 v3, v3, v6, vcc
	v_sub_u32_e32 v6, v5, v4
	v_cndmask_b32_e32 v5, v5, v6, vcc
	v_add_u32_e32 v6, 1, v3
	v_cmp_ge_u32_e32 vcc, v5, v4
	v_add_u32_e32 v5, 1, v7
	s_nop 0
	v_cndmask_b32_e32 v3, v3, v6, vcc
	v_mul_lo_u32 v6, v4, v3
	v_add_u32_e32 v4, v6, v4
	v_cmp_ne_u32_e32 vcc, v5, v4
	s_and_saveexec_b64 s[2:3], vcc
	s_xor_b64 s[2:3], exec, s[2:3]
	s_cbranch_execz .LBB0_227
	v_readlane_b32 s4, v251, 30
	v_readlane_b32 s5, v251, 31
	s_waitcnt lgkmcnt(0)
	s_nop 3
	global_load_dword v2, v99, s[4:5] sc1
	s_waitcnt vmcnt(0)
	v_cmp_eq_u32_e32 vcc, v2, v3
	s_and_saveexec_b64 s[4:5], vcc
	s_cbranch_execz .LBB0_226
	s_mov_b32 s10, 1
	s_mov_b64 s[8:9], 0
	s_branch .LBB0_217

; __device__ __forceinline__ unsigned xb_ld(unsigned* p)              { return __hip_atomic_load(p, __ATOMIC_RELAXED, __HIP_MEMORY_SCOPE_AGENT); }
; #define XB_SPIN(cond, bar) do { unsigned _sp = 0; while (cond) { __builtin_amdgcn_s_sleep(1); \
;     if ((++_sp & 255u) == 0u) { if (xb_ld(&(bar)[XB_TMO])) break; if (_sp > XB_SPIN_CAP) { atomicAdd(&(bar)[XB_TMO], 1u); break; } } } } while (0)
; __device__ __forceinline__ void xcd_barrier(const XcdBarrier& b) {
;     ...
;         } else {
;             XB_SPIN(xb_ld(&bar[XB_XGEN(b.x)]) == gen, bar);
;             __builtin_amdgcn_fence(__ATOMIC_ACQUIRE, "agent");
;             asm volatile("s_waitcnt vmcnt(0)" ::: "memory");
;         }
.LBB0_226:
	s_or_b64 exec, exec, s[4:5]
	s_waitcnt vmcnt(0)
	s_waitcnt vmcnt(0)

; __device__ __forceinline__ unsigned xb_add(unsigned* p, unsigned v) { return __hip_atomic_fetch_add(p, v, __ATOMIC_RELAXED, __HIP_MEMORY_SCOPE_AGENT); }
; __device__ __forceinline__ void xcd_barrier(const XcdBarrier& b) {
;     ...
;             __builtin_amdgcn_fence(__ATOMIC_ACQUIRE, "agent");
;             xb_add(&bar[XB_XGEN(b.x)], 1u);
;             asm volatile("s_waitcnt vmcnt(0)" ::: "memory");
.LBB0_244:
	s_or_b64 exec, exec, s[2:3]
	s_mov_b64 s[2:3], exec
	v_mbcnt_lo_u32_b32 v2, s2, 0
	v_mbcnt_hi_u32_b32 v2, s3, v2
	v_cmp_eq_u32_e32 vcc, 0, v2
	s_waitcnt vmcnt(0)
	s_and_saveexec_b64 s[4:5], vcc
	s_cbranch_execz .LBB0_246
	s_bcnt1_i32_b64 s2, s[2:3]
	v_mov_b32_e32 v2, s2
	v_readlane_b32 s2, v251, 30
	v_readlane_b32 s3, v251, 31
	s_nop 4
	global_atomic_add v99, v2, s[2:3]
.LBB0_246:
	s_or_b64 exec, exec, s[4:5]
	s_waitcnt vmcnt(0)

; __device__ __forceinline__ unsigned xb_add(unsigned* p, unsigned v) { return __hip_atomic_fetch_add(p, v, __ATOMIC_RELAXED, __HIP_MEMORY_SCOPE_AGENT); }
; __device__ __forceinline__ void xcd_barrier(const XcdBarrier& b) {
;     ...
;             __builtin_amdgcn_fence(__ATOMIC_ACQUIRE, "agent");
;             xb_add(&bar[XB_XGEN(b.x)], 1u);
;             asm volatile("s_waitcnt vmcnt(0)" ::: "memory");
.LBB0_392:
	s_or_b64 exec, exec, s[2:3]
	s_mov_b64 s[2:3], exec
	v_mbcnt_lo_u32_b32 v2, s2, 0
	v_mbcnt_hi_u32_b32 v2, s3, v2
	v_cmp_eq_u32_e32 vcc, 0, v2
	s_waitcnt vmcnt(0)
	s_and_saveexec_b64 s[4:5], vcc
	s_cbranch_execz .LBB0_394
	s_bcnt1_i32_b64 s2, s[2:3]
	v_mov_b32_e32 v2, s2
	v_readlane_b32 s2, v251, 30
	v_readlane_b32 s3, v251, 31
	s_nop 4
	global_atomic_add v99, v2, s[2:3]
.LBB0_394:
	s_or_b64 exec, exec, s[4:5]
	s_waitcnt vmcnt(0)

; __device__ __forceinline__ unsigned xb_ld(unsigned* p)              { return __hip_atomic_load(p, __ATOMIC_RELAXED, __HIP_MEMORY_SCOPE_AGENT); }
; __device__ __forceinline__ unsigned xb_add(unsigned* p, unsigned v) { return __hip_atomic_fetch_add(p, v, __ATOMIC_RELAXED, __HIP_MEMORY_SCOPE_AGENT); }
; #define XB_SPIN(cond, bar) do { unsigned _sp = 0; while (cond) { __builtin_amdgcn_s_sleep(1); \
;     if ((++_sp & 255u) == 0u) { if (xb_ld(&(bar)[XB_TMO])) break; if (_sp > XB_SPIN_CAP) { atomicAdd(&(bar)[XB_TMO], 1u); break; } } } } while (0)
; __device__ __forceinline__ void xcd_barrier(const XcdBarrier& b) {
;     ...
;         unsigned nloc = b.st[0], nx = b.st[1];
;         if (nloc == 0u) { xcd_barrier_complete(bar, b.x, nloc, nx, b.members); b.st[0] = nloc; b.st[1] = nx; }
;         const unsigned old = xb_add(&bar[XB_XSUB(b.x)], 1u);
;         const unsigned gen = old / nloc;
;         if (old + 1u == (gen + 1u) * nloc) {
;             __builtin_amdgcn_fence(__ATOMIC_RELEASE, "agent");
;             asm volatile("s_waitcnt vmcnt(0)" ::: "memory");
;             const unsigned og = xb_add(&bar[XB_TOP], 1u);
;             const unsigned tg = og / nx;
;             if (og + 1u == (tg + 1u) * nx) xb_add(&bar[XB_TOPGEN], 1u);
;             else XB_SPIN(xb_ld(&bar[XB_TOPGEN]) == tg, bar);
;             __builtin_amdgcn_fence(__ATOMIC_ACQUIRE, "agent");
;             xb_add(&bar[XB_XGEN(b.x)], 1u);
;             asm volatile("s_waitcnt vmcnt(0)" ::: "memory");
;         } else {
;             XB_SPIN(xb_ld(&bar[XB_XGEN(b.x)]) == gen, bar);
;             __builtin_amdgcn_fence(__ATOMIC_ACQUIRE, "agent");
;             asm volatile("s_waitcnt vmcnt(0)" ::: "memory");
;         }
.LBB0_587:
	s_mov_b64 s[6:7], exec
	v_mbcnt_lo_u32_b32 v3, s6, 0
	v_mbcnt_hi_u32_b32 v3, s7, v3
	v_cmp_eq_u32_e32 vcc, 0, v3
	s_and_saveexec_b64 s[4:5], vcc
	s_cbranch_execz .LBB0_589
	s_bcnt1_i32_b64 s6, s[6:7]
	v_mov_b32_e32 v5, s6
	v_readlane_b32 s6, v251, 28
	v_readlane_b32 s7, v251, 29
	s_nop 4
	global_atomic_add v5, v99, v5, s[6:7] sc0
	buffer_inv sc1
.LBB0_589:
	s_or_b64 exec, exec, s[4:5]
	v_cvt_f32_u32_e32 v6, v4
	s_waitcnt vmcnt(1)
	v_readfirstlane_b32 s4, v5
	v_sub_u32_e32 v5, 0, v4
	v_rcp_iflag_f32_e32 v6, v6
	v_add_u32_e32 v7, s4, v3
	v_mul_f32_e32 v6, 0x4f7ffffe, v6
	v_cvt_u32_f32_e32 v6, v6
	v_mul_lo_u32 v3, v5, v6
	v_mul_hi_u32 v3, v6, v3
	v_add_u32_e32 v3, v6, v3
	v_mul_hi_u32 v3, v7, v3
	v_mul_lo_u32 v5, v3, v4
	v_sub_u32_e32 v5, v7, v5
	v_add_u32_e32 v6, 1, v3
	v_cmp_ge_u32_e32 vcc, v5, v4
	s_nop 1
	v_cndmask_b32_e32 v3, v3, v6, vcc
	v_sub_u32_e32 v6, v5, v4
	v_cndmask_b32_e32 v5, v5, v6, vcc
	v_add_u32_e32 v6, 1, v3
	v_cmp_ge_u32_e32 vcc, v5, v4
	v_add_u32_e32 v5, 1, v7
	s_nop 0
	v_cndmask_b32_e32 v3, v3, v6, vcc
	v_mul_lo_u32 v6, v4, v3
	v_add_u32_e32 v4, v6, v4
	v_cmp_ne_u32_e32 vcc, v5, v4
	s_and_saveexec_b64 s[4:5], vcc
	s_xor_b64 s[4:5], exec, s[4:5]
	s_cbranch_execz .LBB0_603
	v_readlane_b32 s6, v251, 30
	v_readlane_b32 s7, v251, 31
	s_waitcnt lgkmcnt(0)
	s_nop 3
	global_load_dword v2, v99, s[6:7] sc1
	s_waitcnt vmcnt(0)
	v_cmp_eq_u32_e32 vcc, v2, v3
	s_and_saveexec_b64 s[6:7], vcc
	s_cbranch_execz .LBB0_602
	s_mov_b32 s20, 1
	s_mov_b64 s[8:9], 0
	s_branch .LBB0_593

; __device__ __forceinline__ unsigned xb_ld(unsigned* p)              { return __hip_atomic_load(p, __ATOMIC_RELAXED, __HIP_MEMORY_SCOPE_AGENT); }
; #define XB_SPIN(cond, bar) do { unsigned _sp = 0; while (cond) { __builtin_amdgcn_s_sleep(1); \
;     if ((++_sp & 255u) == 0u) { if (xb_ld(&(bar)[XB_TMO])) break; if (_sp > XB_SPIN_CAP) { atomicAdd(&(bar)[XB_TMO], 1u); break; } } } } while (0)
; __device__ __forceinline__ void xcd_barrier(const XcdBarrier& b) {
;     ...
;         } else {
;             XB_SPIN(xb_ld(&bar[XB_XGEN(b.x)]) == gen, bar);
;             __builtin_amdgcn_fence(__ATOMIC_ACQUIRE, "agent");
;             asm volatile("s_waitcnt vmcnt(0)" ::: "memory");
;         }
.LBB0_602:
	s_or_b64 exec, exec, s[6:7]
	s_waitcnt vmcnt(0)
	s_waitcnt vmcnt(0)

; __device__ __forceinline__ unsigned xb_add(unsigned* p, unsigned v) { return __hip_atomic_fetch_add(p, v, __ATOMIC_RELAXED, __HIP_MEMORY_SCOPE_AGENT); }
; __device__ __forceinline__ void xcd_barrier(const XcdBarrier& b) {
;     ...
;             __builtin_amdgcn_fence(__ATOMIC_ACQUIRE, "agent");
;             xb_add(&bar[XB_XGEN(b.x)], 1u);
;             asm volatile("s_waitcnt vmcnt(0)" ::: "memory");
.LBB0_620:
	s_or_b64 exec, exec, s[4:5]
	s_mov_b64 s[4:5], exec
	v_mbcnt_lo_u32_b32 v2, s4, 0
	v_mbcnt_hi_u32_b32 v2, s5, v2
	v_cmp_eq_u32_e32 vcc, 0, v2
	s_waitcnt vmcnt(0)
	s_and_saveexec_b64 s[6:7], vcc
	s_cbranch_execz .LBB0_622
	s_bcnt1_i32_b64 s4, s[4:5]
	v_mov_b32_e32 v2, s4
	v_readlane_b32 s4, v251, 30
	v_readlane_b32 s5, v251, 31
	s_nop 4
	global_atomic_add v99, v2, s[4:5]
.LBB0_622:
	s_or_b64 exec, exec, s[6:7]
	s_waitcnt vmcnt(0)

; __device__ __forceinline__ unsigned xb_ld(unsigned* p)              { return __hip_atomic_load(p, __ATOMIC_RELAXED, __HIP_MEMORY_SCOPE_AGENT); }
; __device__ __forceinline__ unsigned xb_add(unsigned* p, unsigned v) { return __hip_atomic_fetch_add(p, v, __ATOMIC_RELAXED, __HIP_MEMORY_SCOPE_AGENT); }
; #define XB_SPIN(cond, bar) do { unsigned _sp = 0; while (cond) { __builtin_amdgcn_s_sleep(1); \
;     if ((++_sp & 255u) == 0u) { if (xb_ld(&(bar)[XB_TMO])) break; if (_sp > XB_SPIN_CAP) { atomicAdd(&(bar)[XB_TMO], 1u); break; } } } } while (0)
; __device__ __forceinline__ void xcd_barrier(const XcdBarrier& b) {
;     ...
;         unsigned nloc = b.st[0], nx = b.st[1];
;         if (nloc == 0u) { xcd_barrier_complete(bar, b.x, nloc, nx, b.members); b.st[0] = nloc; b.st[1] = nx; }
;         const unsigned old = xb_add(&bar[XB_XSUB(b.x)], 1u);
;         const unsigned gen = old / nloc;
;         if (old + 1u == (gen + 1u) * nloc) {
;             __builtin_amdgcn_fence(__ATOMIC_RELEASE, "agent");
;             asm volatile("s_waitcnt vmcnt(0)" ::: "memory");
;             const unsigned og = xb_add(&bar[XB_TOP], 1u);
;             const unsigned tg = og / nx;
;             if (og + 1u == (tg + 1u) * nx) xb_add(&bar[XB_TOPGEN], 1u);
;             else XB_SPIN(xb_ld(&bar[XB_TOPGEN]) == tg, bar);
;             __builtin_amdgcn_fence(__ATOMIC_ACQUIRE, "agent");
;             xb_add(&bar[XB_XGEN(b.x)], 1u);
;             asm volatile("s_waitcnt vmcnt(0)" ::: "memory");
;         } else {
;             XB_SPIN(xb_ld(&bar[XB_XGEN(b.x)]) == gen, bar);
;             __builtin_amdgcn_fence(__ATOMIC_ACQUIRE, "agent");
;             asm volatile("s_waitcnt vmcnt(0)" ::: "memory");
;         }
.LBB0_662:
	v_readlane_b32 s2, v252, 40
	v_readlane_b32 s3, v252, 41
	v_cvt_f32_u32_e32 v2, v4
	v_sub_u32_e32 v6, 0, v4
	v_rcp_iflag_f32_e32 v2, v2
	s_nop 1
	global_atomic_add v5, v99, v215, s[2:3] sc0
	buffer_inv sc1
	v_mul_f32_e32 v2, 0x4f7ffffe, v2
	v_cvt_u32_f32_e32 v2, v2
	v_mul_lo_u32 v6, v6, v2
	v_mul_hi_u32 v6, v2, v6
	v_add_u32_e32 v2, v2, v6
	s_waitcnt vmcnt(1)
	v_mul_hi_u32 v2, v5, v2
	v_mul_lo_u32 v6, v2, v4
	v_sub_u32_e32 v6, v5, v6
	v_add_u32_e32 v7, 1, v2
	v_cmp_ge_u32_e32 vcc, v6, v4
	v_add_u32_e32 v5, 1, v5
	s_nop 0
	v_cndmask_b32_e32 v2, v2, v7, vcc
	v_sub_u32_e32 v7, v6, v4
	v_cndmask_b32_e32 v6, v6, v7, vcc
	v_add_u32_e32 v7, 1, v2
	v_cmp_ge_u32_e32 vcc, v6, v4
	s_nop 1
	v_cndmask_b32_e32 v2, v2, v7, vcc
	v_mul_lo_u32 v6, v4, v2
	v_add_u32_e32 v4, v6, v4
	v_cmp_ne_u32_e32 vcc, v5, v4
	s_and_saveexec_b64 s[2:3], vcc
	s_xor_b64 s[2:3], exec, s[2:3]
	s_cbranch_execz .LBB0_675
	v_readlane_b32 s4, v252, 42
	v_readlane_b32 s5, v252, 43
	s_waitcnt lgkmcnt(0)
	s_nop 3
	global_load_dword v3, v99, s[4:5] sc1
	s_waitcnt vmcnt(0)
	v_cmp_eq_u32_e32 vcc, v3, v2
	s_and_saveexec_b64 s[4:5], vcc
	s_cbranch_execz .LBB0_674
	s_mov_b32 s18, 1
	s_mov_b64 s[6:7], 0
	s_branch .LBB0_666

; __device__ __forceinline__ unsigned xb_add(unsigned* p, unsigned v) { return __hip_atomic_fetch_add(p, v, __ATOMIC_RELAXED, __HIP_MEMORY_SCOPE_AGENT); }
; __device__ __forceinline__ void xcd_barrier(const XcdBarrier& b) {
;     ...
;             __builtin_amdgcn_fence(__ATOMIC_ACQUIRE, "agent");
;             xb_add(&bar[XB_XGEN(b.x)], 1u);
;             asm volatile("s_waitcnt vmcnt(0)" ::: "memory");
.Lgb_fast0:
	v_readlane_b32 s2, v252, 42
	v_readlane_b32 s3, v252, 43
	s_nop 0
	s_nop 3
	global_atomic_add v99, v215, s[2:3]
	s_waitcnt vmcnt(0)

; __device__ __forceinline__ unsigned xb_ld(unsigned* p)              { return __hip_atomic_load(p, __ATOMIC_RELAXED, __HIP_MEMORY_SCOPE_AGENT); }
; __device__ __forceinline__ unsigned xb_add(unsigned* p, unsigned v) { return __hip_atomic_fetch_add(p, v, __ATOMIC_RELAXED, __HIP_MEMORY_SCOPE_AGENT); }
; #define XB_SPIN(cond, bar) do { unsigned _sp = 0; while (cond) { __builtin_amdgcn_s_sleep(1); \
;     if ((++_sp & 255u) == 0u) { if (xb_ld(&(bar)[XB_TMO])) break; if (_sp > XB_SPIN_CAP) { atomicAdd(&(bar)[XB_TMO], 1u); break; } } } } while (0)
; __device__ __forceinline__ void xcd_barrier(const XcdBarrier& b) {
;     ...
;         unsigned nloc = b.st[0], nx = b.st[1];
;         if (nloc == 0u) { xcd_barrier_complete(bar, b.x, nloc, nx, b.members); b.st[0] = nloc; b.st[1] = nx; }
;         const unsigned old = xb_add(&bar[XB_XSUB(b.x)], 1u);
;         const unsigned gen = old / nloc;
;         if (old + 1u == (gen + 1u) * nloc) {
;             __builtin_amdgcn_fence(__ATOMIC_RELEASE, "agent");
;             asm volatile("s_waitcnt vmcnt(0)" ::: "memory");
;             const unsigned og = xb_add(&bar[XB_TOP], 1u);
;             const unsigned tg = og / nx;
;             if (og + 1u == (tg + 1u) * nx) xb_add(&bar[XB_TOPGEN], 1u);
;             else XB_SPIN(xb_ld(&bar[XB_TOPGEN]) == tg, bar);
;             __builtin_amdgcn_fence(__ATOMIC_ACQUIRE, "agent");
;             xb_add(&bar[XB_XGEN(b.x)], 1u);
;             asm volatile("s_waitcnt vmcnt(0)" ::: "memory");
;         } else {
;             XB_SPIN(xb_ld(&bar[XB_XGEN(b.x)]) == gen, bar);
;             __builtin_amdgcn_fence(__ATOMIC_ACQUIRE, "agent");
;             asm volatile("s_waitcnt vmcnt(0)" ::: "memory");
;         }
.LBB0_931:
	s_or_b64 exec, exec, s[2:3]
	v_cvt_f32_u32_e32 v6, v4
	s_waitcnt vmcnt(1)
	v_readfirstlane_b32 s2, v5
	v_sub_u32_e32 v5, 0, v4
	v_rcp_iflag_f32_e32 v6, v6
	v_add_u32_e32 v7, s2, v3
	v_mul_f32_e32 v6, 0x4f7ffffe, v6
	v_cvt_u32_f32_e32 v6, v6
	v_mul_lo_u32 v3, v5, v6
	v_mul_hi_u32 v3, v6, v3
	v_add_u32_e32 v3, v6, v3
	v_mul_hi_u32 v3, v7, v3
	v_mul_lo_u32 v5, v3, v4
	v_sub_u32_e32 v5, v7, v5
	v_add_u32_e32 v6, 1, v3
	v_cmp_ge_u32_e32 vcc, v5, v4
	s_nop 1
	v_cndmask_b32_e32 v3, v3, v6, vcc
	v_sub_u32_e32 v6, v5, v4
	v_cndmask_b32_e32 v5, v5, v6, vcc
	v_add_u32_e32 v6, 1, v3
	v_cmp_ge_u32_e32 vcc, v5, v4
	v_add_u32_e32 v5, 1, v7
	s_nop 0
	v_cndmask_b32_e32 v3, v3, v6, vcc
	v_mul_lo_u32 v6, v4, v3
	v_add_u32_e32 v4, v6, v4
	v_cmp_ne_u32_e32 vcc, v5, v4
	s_and_saveexec_b64 s[2:3], vcc
	s_xor_b64 s[2:3], exec, s[2:3]
	s_cbranch_execz .LBB0_945
	v_readlane_b32 s4, v251, 30
	v_readlane_b32 s5, v251, 31
	s_waitcnt lgkmcnt(0)
	s_nop 3
	global_load_dword v2, v99, s[4:5] sc1
	s_waitcnt vmcnt(0)
	v_cmp_eq_u32_e32 vcc, v2, v3
	s_and_saveexec_b64 s[4:5], vcc
	s_cbranch_execz .LBB0_944
	s_mov_b32 s18, 1
	s_mov_b64 s[6:7], 0
	s_branch .LBB0_935

; __device__ __forceinline__ unsigned xb_add(unsigned* p, unsigned v) { return __hip_atomic_fetch_add(p, v, __ATOMIC_RELAXED, __HIP_MEMORY_SCOPE_AGENT); }
; __device__ __forceinline__ void xcd_barrier(const XcdBarrier& b) {
;     ...
;             __builtin_amdgcn_fence(__ATOMIC_ACQUIRE, "agent");
;             xb_add(&bar[XB_XGEN(b.x)], 1u);
;             asm volatile("s_waitcnt vmcnt(0)" ::: "memory");
.LBB0_962:
	s_or_b64 exec, exec, s[2:3]
	s_mov_b64 s[2:3], exec
	v_mbcnt_lo_u32_b32 v2, s2, 0
	v_mbcnt_hi_u32_b32 v2, s3, v2
	v_cmp_eq_u32_e32 vcc, 0, v2
	s_waitcnt vmcnt(0)
	s_and_saveexec_b64 s[4:5], vcc
	s_cbranch_execz .LBB0_964
	s_bcnt1_i32_b64 s2, s[2:3]
	v_mov_b32_e32 v2, s2
	v_readlane_b32 s2, v251, 30
	v_readlane_b32 s3, v251, 31
	s_nop 4
	global_atomic_add v99, v2, s[2:3]
.LBB0_964:
	s_or_b64 exec, exec, s[4:5]
	s_waitcnt vmcnt(0)

; __device__ __forceinline__ unsigned xb_ld(unsigned* p)              { return __hip_atomic_load(p, __ATOMIC_RELAXED, __HIP_MEMORY_SCOPE_AGENT); }
; __device__ __forceinline__ unsigned xb_add(unsigned* p, unsigned v) { return __hip_atomic_fetch_add(p, v, __ATOMIC_RELAXED, __HIP_MEMORY_SCOPE_AGENT); }
; #define XB_SPIN(cond, bar) do { unsigned _sp = 0; while (cond) { __builtin_amdgcn_s_sleep(1); \
;     if ((++_sp & 255u) == 0u) { if (xb_ld(&(bar)[XB_TMO])) break; if (_sp > XB_SPIN_CAP) { atomicAdd(&(bar)[XB_TMO], 1u); break; } } } } while (0)
; __device__ __forceinline__ void xcd_barrier(const XcdBarrier& b) {
;     ...
;         unsigned nloc = b.st[0], nx = b.st[1];
;         if (nloc == 0u) { xcd_barrier_complete(bar, b.x, nloc, nx, b.members); b.st[0] = nloc; b.st[1] = nx; }
;         const unsigned old = xb_add(&bar[XB_XSUB(b.x)], 1u);
;         const unsigned gen = old / nloc;
;         if (old + 1u == (gen + 1u) * nloc) {
;             __builtin_amdgcn_fence(__ATOMIC_RELEASE, "agent");
;             asm volatile("s_waitcnt vmcnt(0)" ::: "memory");
;             const unsigned og = xb_add(&bar[XB_TOP], 1u);
;             const unsigned tg = og / nx;
;             if (og + 1u == (tg + 1u) * nx) xb_add(&bar[XB_TOPGEN], 1u);
;             else XB_SPIN(xb_ld(&bar[XB_TOPGEN]) == tg, bar);
;             __builtin_amdgcn_fence(__ATOMIC_ACQUIRE, "agent");
;             xb_add(&bar[XB_XGEN(b.x)], 1u);
;             asm volatile("s_waitcnt vmcnt(0)" ::: "memory");
;         } else {
;             XB_SPIN(xb_ld(&bar[XB_XGEN(b.x)]) == gen, bar);
;             __builtin_amdgcn_fence(__ATOMIC_ACQUIRE, "agent");
;             asm volatile("s_waitcnt vmcnt(0)" ::: "memory");
;         }
.LBB0_1071:
	v_readlane_b32 s2, v252, 40
	v_readlane_b32 s3, v252, 41
	v_cvt_f32_u32_e32 v2, v4
	v_sub_u32_e32 v6, 0, v4
	v_rcp_iflag_f32_e32 v2, v2
	s_nop 1
	global_atomic_add v5, v99, v215, s[2:3] sc0
	buffer_inv sc1
	v_mul_f32_e32 v2, 0x4f7ffffe, v2
	v_cvt_u32_f32_e32 v2, v2
	v_mul_lo_u32 v6, v6, v2
	v_mul_hi_u32 v6, v2, v6
	v_add_u32_e32 v2, v2, v6
	s_waitcnt vmcnt(1)
	v_mul_hi_u32 v2, v5, v2
	v_mul_lo_u32 v6, v2, v4
	v_sub_u32_e32 v6, v5, v6
	v_add_u32_e32 v7, 1, v2
	v_cmp_ge_u32_e32 vcc, v6, v4
	v_add_u32_e32 v5, 1, v5
	s_nop 0
	v_cndmask_b32_e32 v2, v2, v7, vcc
	v_sub_u32_e32 v7, v6, v4
	v_cndmask_b32_e32 v6, v6, v7, vcc
	v_add_u32_e32 v7, 1, v2
	v_cmp_ge_u32_e32 vcc, v6, v4
	s_nop 1
	v_cndmask_b32_e32 v2, v2, v7, vcc
	v_mul_lo_u32 v6, v4, v2
	v_add_u32_e32 v4, v6, v4
	v_cmp_ne_u32_e32 vcc, v5, v4
	s_and_saveexec_b64 s[2:3], vcc
	s_xor_b64 s[2:3], exec, s[2:3]
	s_cbranch_execz .LBB0_1084
	v_readlane_b32 s4, v252, 42
	v_readlane_b32 s5, v252, 43
	s_waitcnt lgkmcnt(0)
	s_nop 3
	global_load_dword v3, v99, s[4:5] sc1
	s_waitcnt vmcnt(0)
	v_cmp_eq_u32_e32 vcc, v3, v2
	s_and_saveexec_b64 s[4:5], vcc
	s_cbranch_execz .LBB0_1083
	s_mov_b32 s10, 1
	s_mov_b64 s[8:9], 0
	s_branch .LBB0_1075

; __device__ __forceinline__ unsigned xb_ld(unsigned* p)              { return __hip_atomic_load(p, __ATOMIC_RELAXED, __HIP_MEMORY_SCOPE_AGENT); }
; __device__ __forceinline__ unsigned xb_add(unsigned* p, unsigned v) { return __hip_atomic_fetch_add(p, v, __ATOMIC_RELAXED, __HIP_MEMORY_SCOPE_AGENT); }
; #define XB_SPIN(cond, bar) do { unsigned _sp = 0; while (cond) { __builtin_amdgcn_s_sleep(1); \
;     if ((++_sp & 255u) == 0u) { if (xb_ld(&(bar)[XB_TMO])) break; if (_sp > XB_SPIN_CAP) { atomicAdd(&(bar)[XB_TMO], 1u); break; } } } } while (0)
; __device__ __forceinline__ void xcd_barrier(const XcdBarrier& b) {
;     ...
;         unsigned nloc = b.st[0], nx = b.st[1];
;         if (nloc == 0u) { xcd_barrier_complete(bar, b.x, nloc, nx, b.members); b.st[0] = nloc; b.st[1] = nx; }
;         const unsigned old = xb_add(&bar[XB_XSUB(b.x)], 1u);
;         const unsigned gen = old / nloc;
;         if (old + 1u == (gen + 1u) * nloc) {
;             __builtin_amdgcn_fence(__ATOMIC_RELEASE, "agent");
;             asm volatile("s_waitcnt vmcnt(0)" ::: "memory");
;             const unsigned og = xb_add(&bar[XB_TOP], 1u);
;             const unsigned tg = og / nx;
;             if (og + 1u == (tg + 1u) * nx) xb_add(&bar[XB_TOPGEN], 1u);
;             else XB_SPIN(xb_ld(&bar[XB_TOPGEN]) == tg, bar);
;             __builtin_amdgcn_fence(__ATOMIC_ACQUIRE, "agent");
;             xb_add(&bar[XB_XGEN(b.x)], 1u);
;             asm volatile("s_waitcnt vmcnt(0)" ::: "memory");
;         } else {
;             XB_SPIN(xb_ld(&bar[XB_XGEN(b.x)]) == gen, bar);
;             __builtin_amdgcn_fence(__ATOMIC_ACQUIRE, "agent");
;             asm volatile("s_waitcnt vmcnt(0)" ::: "memory");
;         }
.LBB0_1118:
	v_readlane_b32 s4, v252, 40
	v_readlane_b32 s5, v252, 41
	v_cvt_f32_u32_e32 v2, v4
	v_sub_u32_e32 v6, 0, v4
	v_rcp_iflag_f32_e32 v2, v2
	s_nop 1
	global_atomic_add v5, v99, v215, s[4:5] sc0
	buffer_inv sc1
	v_mul_f32_e32 v2, 0x4f7ffffe, v2
	v_cvt_u32_f32_e32 v2, v2
	v_mul_lo_u32 v6, v6, v2
	v_mul_hi_u32 v6, v2, v6
	v_add_u32_e32 v2, v2, v6
	s_waitcnt vmcnt(1)
	v_mul_hi_u32 v2, v5, v2
	v_mul_lo_u32 v6, v2, v4
	v_sub_u32_e32 v6, v5, v6
	v_add_u32_e32 v7, 1, v2
	v_cmp_ge_u32_e32 vcc, v6, v4
	v_add_u32_e32 v5, 1, v5
	s_nop 0
	v_cndmask_b32_e32 v2, v2, v7, vcc
	v_sub_u32_e32 v7, v6, v4
	v_cndmask_b32_e32 v6, v6, v7, vcc
	v_add_u32_e32 v7, 1, v2
	v_cmp_ge_u32_e32 vcc, v6, v4
	s_nop 1
	v_cndmask_b32_e32 v2, v2, v7, vcc
	v_mul_lo_u32 v6, v4, v2
	v_add_u32_e32 v4, v6, v4
	v_cmp_ne_u32_e32 vcc, v5, v4
	s_and_saveexec_b64 s[4:5], vcc
	s_xor_b64 s[4:5], exec, s[4:5]
	s_cbranch_execz .LBB0_1131
	v_readlane_b32 s6, v252, 42
	v_readlane_b32 s7, v252, 43
	s_waitcnt lgkmcnt(0)
	s_nop 3
	global_load_dword v3, v99, s[6:7] sc1
	s_waitcnt vmcnt(0)
	v_cmp_eq_u32_e32 vcc, v3, v2
	s_and_saveexec_b64 s[6:7], vcc
	s_cbranch_execz .LBB0_1130
	s_mov_b32 s20, 1
	s_mov_b64 s[8:9], 0
	s_branch .LBB0_1122

; __device__ __forceinline__ unsigned xb_add(unsigned* p, unsigned v) { return __hip_atomic_fetch_add(p, v, __ATOMIC_RELAXED, __HIP_MEMORY_SCOPE_AGENT); }
; __device__ __forceinline__ void xcd_barrier(const XcdBarrier& b) {
;     ...
;             __builtin_amdgcn_fence(__ATOMIC_ACQUIRE, "agent");
;             xb_add(&bar[XB_XGEN(b.x)], 1u);
;             asm volatile("s_waitcnt vmcnt(0)" ::: "memory");
.Lgb_fast5:
	v_readlane_b32 s4, v252, 42
	v_readlane_b32 s5, v252, 43
	s_nop 0
	s_nop 3
	global_atomic_add v99, v215, s[4:5]
	s_waitcnt vmcnt(0)
